# sample attention PV also on f32 MFMA; K prefetched at unit entry, V prefetched before softmax
# speedup vs baseline: 1.0457x; 1.0031x over previous
; #define LAS __attribute__((address_space(3)))
; __device__ __forceinline__ void attn_sample_unit(LAS unsigned char* lds, CArgsP a, int b, int h) {
;     const int tid = threadIdx.x, lane = tid & 63, wid = tid >> 6;
;     LAS float* C = (LAS float*)(lds + SA_C); LAS float* Qs = (LAS float*)(lds + SA_Q); LAS float* SC = (LAS float*)(lds + SA_SC);
;     const float* LOGF = (const float*)(a->ws + WS_LOGF); const bf16_t* QB = (const bf16_t*)(a->ws + WS_Q); bf16_t* MIX = (bf16_t*)(a->ws + WS_XB);
;     const float* ck = a->in[2]; const float* cv = a->in[3]; const float* clf = a->in[4];
;     const float* nk = a->out + OFF_KS; const float* nv = a->out + OFF_VS;
;     __syncthreads();
;     if (wid == 0) {
;         float v[17]; float run = 0.f;
; #pragma unroll
;         for (int i = 0; i < 17; ++i) {
;             const int j = 17 * lane + i; float x = 0.f;
;             if (j < PAST) x = clf[((size_t)b * PAST + j) * 8 + h]; else if (j < SA_NK) x = LOGF[(size_t)(TP + 16 * b + (j - PAST)) * 8 + h];
;             run += x; v[i] = run;
;         }
;         float inc = run;
; #pragma unroll
;         for (int o = 1; o < 64; o <<= 1) { const float t = __shfl_up(inc, o); if (lane >= o) inc += t; }
;         const float excl = inc - run;
; #pragma unroll
;         for (int i = 0; i < 17; ++i) { const int j = 17 * lane + i; if (j < SA_NK) C[j] = excl + v[i]; }
;     } else {
;         for (int i = tid - 64; i < 1024; i += 448) { const int t = i >> 6, d = i & 63; Qs[i] = bf2f(QB[(size_t)(TP + 16 * b + t) * 512 + h * 64 + d]); }
;     }
;     __syncthreads();
;     for (int j = tid; j < SA_NK; j += 512) {
;         const float* kp = j < PAST ? ck + (((size_t)b * PAST + j) * 8 + h) * 64 : nk + (size_t)(16 * b + (j - PAST)) * 512 + h * 64;
;         float acc[16];
; #pragma unroll
;         for (int t = 0; t < 16; ++t) acc[t] = 0.f;
; #pragma unroll
;         for (int hb = 0; hb < 2; ++hb) {
;             f32x4 kr[8];
; #pragma unroll
;             for (int i = 0; i < 8; ++i) kr[i] = *(const f32x4*)(kp + 32 * hb + 4 * i);
.LBB0_1241:
	s_cmpk_gt_u32 s0, 0x7f
	s_cselect_b64 s[4:5], -1, 0
	s_or_b64 s[4:5], s[4:5], s[22:23]
	s_and_b64 vcc, exec, s[4:5]
	s_cbranch_vccnz .LBB0_1433
	s_load_dwordx4 s[12:15], s[20:21], 0xf0
	s_load_dwordx4 s[16:19], s[20:21], 0x10
	s_load_dwordx2 s[8:9], s[20:21], 0x20
	s_lshr_b32 s24, s0, 3
	v_readlane_b32 s6, v250, 0
	s_and_b32 s10, s2, 7
	s_lshl_b32 s0, s24, 4
	v_readlane_b32 s7, v250, 1
	s_waitcnt lgkmcnt(0)
	s_barrier
	v_readfirstlane_b32 s46, v50
	v_lshrrev_b32_e32 v137, 4, v148
	v_and_b32_e32 v138, 15, v148
	v_lshlrev_b32_e32 v136, 11, v138
	v_lshl_add_u32 v136, v137, 4, v136
	s_lshl_b32 s48, s24, 21
	s_lshl_b32 s49, s10, 8
	s_add_u32 s48, s48, s49
	s_lshl_b32 s50, s46, 15
	s_add_u32 s48, s48, s50
	s_add_u32 s38, s16, s48
	s_addc_u32 s39, s17, 0
	s_add_u32 s42, s18, s48
	s_addc_u32 s43, s19, 0
	s_lshl_b32 s50, s24, 15
	s_add_u32 s50, s50, s49
	s_add_u32 s40, s12, 0x81a1c00
	s_addc_u32 s41, s13, 0
	s_add_u32 s40, s40, s50
	s_addc_u32 s41, s41, 0
	s_add_u32 s44, s12, 0x8221c00
	s_addc_u32 s45, s13, 0
	s_add_u32 s44, s44, s50
	s_addc_u32 s45, s45, 0
	s_mov_b32 s47, 0x3fb8aa3b
	s_cmp_lg_u32 s46, 0
	s_cbranch_scc1 .Lqk_noext0
	global_load_dwordx4 v[234:237], v136, s[40:41] offset:0
	global_load_dwordx4 v[238:241], v136, s[40:41] offset:64
	global_load_dwordx4 v[242:245], v136, s[40:41] offset:128
	global_load_dwordx4 v[246:249], v136, s[40:41] offset:192
.Lqk_noext0:
	s_add_u32 s48, s38, 0x0
	s_addc_u32 s49, s39, 0
	global_load_dwordx4 v[28:31], v136, s[48:49] offset:0
	global_load_dwordx4 v[32:35], v136, s[48:49] offset:64
	global_load_dwordx4 v[36:39], v136, s[48:49] offset:128
	global_load_dwordx4 v[40:43], v136, s[48:49] offset:192
	s_add_u32 s48, s38, 0x40000
	s_addc_u32 s49, s39, 0
	global_load_dwordx4 v[52:55], v136, s[48:49] offset:0
	global_load_dwordx4 v[56:59], v136, s[48:49] offset:64
	global_load_dwordx4 v[60:63], v136, s[48:49] offset:128
	global_load_dwordx4 v[64:67], v136, s[48:49] offset:192
	s_add_u32 s48, s38, 0x80000
	s_addc_u32 s49, s39, 0
	global_load_dwordx4 v[68:71], v136, s[48:49] offset:0
	global_load_dwordx4 v[72:75], v136, s[48:49] offset:64
	global_load_dwordx4 v[76:79], v136, s[48:49] offset:128
	global_load_dwordx4 v[80:83], v136, s[48:49] offset:192
	s_add_u32 s48, s38, 0xc0000
	s_addc_u32 s49, s39, 0
	global_load_dwordx4 v[84:87], v136, s[48:49] offset:0
	global_load_dwordx4 v[88:91], v136, s[48:49] offset:64
	global_load_dwordx4 v[92:95], v136, s[48:49] offset:128
	global_load_dwordx4 v[96:99], v136, s[48:49] offset:192
	s_add_u32 s48, s38, 0x100000
	s_addc_u32 s49, s39, 0
	global_load_dwordx4 v[104:107], v136, s[48:49] offset:0
	global_load_dwordx4 v[108:111], v136, s[48:49] offset:64
	global_load_dwordx4 v[112:115], v136, s[48:49] offset:128
	global_load_dwordx4 v[116:119], v136, s[48:49] offset:192
	s_add_u32 s48, s38, 0x140000
	s_addc_u32 s49, s39, 0
	global_load_dwordx4 v[120:123], v136, s[48:49] offset:0
	global_load_dwordx4 v[124:127], v136, s[48:49] offset:64
	global_load_dwordx4 v[128:131], v136, s[48:49] offset:128
	global_load_dwordx4 v[132:135], v136, s[48:49] offset:192
	s_add_u32 s48, s38, 0x180000
	s_addc_u32 s49, s39, 0
	global_load_dwordx4 v[202:205], v136, s[48:49] offset:0
	global_load_dwordx4 v[206:209], v136, s[48:49] offset:64
	global_load_dwordx4 v[210:213], v136, s[48:49] offset:128
	global_load_dwordx4 v[214:217], v136, s[48:49] offset:192
	s_add_u32 s48, s38, 0x1c0000
	s_addc_u32 s49, s39, 0
	global_load_dwordx4 v[218:221], v136, s[48:49] offset:0
	global_load_dwordx4 v[222:225], v136, s[48:49] offset:64
	global_load_dwordx4 v[226:229], v136, s[48:49] offset:128
	global_load_dwordx4 v[230:233], v136, s[48:49] offset:192
	s_and_saveexec_b64 s[4:5], s[6:7]
	s_xor_b64 s[6:7], exec, s[4:5]
	s_cbranch_execz .LBB0_1246
	s_or_b32 s1, s0, 0x4000
	s_lshl_b32 s3, s10, 7
	s_add_u32 s4, s14, s3
	s_addc_u32 s5, s15, 0
	v_lshlrev_b32_e32 v0, 1, v148
	v_mov_b32_e32 v1, 0
	v_lshl_add_u64 v[0:1], s[4:5], 0, v[0:1]
	s_mov_b64 s[4:5], 0x5000000
	v_lshl_add_u32 v2, v164, 2, 0
	v_lshl_add_u64 v[0:1], v[0:1], 0, s[4:5]
	v_add_u32_e32 v2, 0x1000, v2
	v_add_u32_e32 v3, 0xfffffe00, v164
	s_mov_b64 s[26:27], 0
	s_movk_i32 s3, 0x23f

; #define LAS __attribute__((address_space(3)))
; __device__ __forceinline__ void attn_sample_unit(LAS unsigned char* lds, CArgsP a, int b, int h) {
;     ...
;     for (int j = tid; j < SA_NK; j += 512) {
;         const float* kp = j < PAST ? ck + (((size_t)b * PAST + j) * 8 + h) * 64 : nk + (size_t)(16 * b + (j - PAST)) * 512 + h * 64;
;         float acc[16];
; #pragma unroll
;         for (int t = 0; t < 16; ++t) acc[t] = 0.f;
; #pragma unroll
;         for (int hb = 0; hb < 2; ++hb) {
;             f32x4 kr[8];
; #pragma unroll
;             for (int i = 0; i < 8; ++i) kr[i] = *(const f32x4*)(kp + 32 * hb + 4 * i);
; #pragma unroll
;             for (int i = 0; i < 8; ++i) {
;                 asm volatile("" ::: "memory");
;                 const f32x4 k4 = kr[i];
; #pragma unroll
;                 for (int t = 0; t < 16; ++t) { const f32x4 q4 = *(const LAS f32x4*)(Qs + t * 64 + 32 * hb + 4 * i); acc[t] += (q4[0] * k4[0] + q4[1] * k4[1]) + (q4[2] * k4[2] + q4[3] * k4[3]); }
;             }
;         }
;         const float cj = C[j];
; #pragma unroll
;         for (int t = 0; t < 16; ++t) SC[t * SA_NK + j] = acc[t] + (C[PAST + t] - cj) * LOG2E;
.LBB0_1348:
	s_or_b64 exec, exec, s[26:27]
	s_lshl_b32 s1, s10, 6
	s_lshl_b32 s3, s10, 8
	s_add_u32 s3, s12, s3
	s_addc_u32 s4, s13, 0
	s_mov_b32 s25, 0
	s_add_u32 s6, s3, 0x81a1c00
	s_addc_u32 s7, s4, 0
	s_lshl_b64 s[4:5], s[24:25], 13
	v_lshl_add_u64 v[0:1], v[0:1], 0, s[4:5]
	v_mov_b32_e32 v151, 0
	v_lshl_add_u64 v[0:1], v[0:1], 0, v[150:151]
	v_lshlrev_b64 v[0:1], 8, v[0:1]
	s_add_i32 s3, s0, 0xfffffc00
	v_lshl_add_u64 v[34:35], s[16:17], 0, v[0:1]
	s_mov_b64 s[8:9], 0
	s_movk_i32 s4, 0x3ff
	s_mov_b64 s[10:11], 0x100000
	s_movk_i32 s5, 0x20f
	v_mov_b32_e32 v38, v164
	s_waitcnt lgkmcnt(0)
	s_barrier
	v_lshrrev_b32_e32 v44, 4, v148
	v_and_b32_e32 v45, 15, v148
	v_lshlrev_b32_e32 v137, 8, v45
	v_lshl_add_u32 v137, v44, 4, v137
	v_lshlrev_b32_e32 v46, 4, v44
	ds_read_b128 v[0:3], v137 offset:4352
	ds_read_b128 v[4:7], v137 offset:4416
	ds_read_b128 v[8:11], v137 offset:4480
	ds_read_b128 v[12:15], v137 offset:4544
	ds_read_b128 v[24:27], v46 offset:4096
	s_lshl_b32 s48, s46, 6
	v_lshl_add_u32 v138, v45, 2, s48
	v_mul_u32_u24_e32 v139, 0x4100, v44
	v_add_u32_e32 v139, v139, v138
	v_add_u32_e32 v139, 0x2100, v139
	v_lshlrev_b32_e32 v47, 13, v44
	v_lshl_add_u32 v47, v45, 4, v47
	s_waitcnt vmcnt(0)
	v_mov_b32_e32 v136, v47
	v_add_u32_e32 v137, 0x1000, v47
	ds_read_b32 v140, v138 offset:0
	ds_read_b32 v141, v138 offset:512
	s_waitcnt lgkmcnt(2)
	v_mfma_f32_16x16x4_f32 v[16:19], v0, v28, 0
	v_mfma_f32_16x16x4_f32 v[20:23], v0, v52, 0
	v_mfma_f32_16x16x4_f32 v[16:19], v1, v29, v[16:19]
	v_mfma_f32_16x16x4_f32 v[20:23], v1, v53, v[20:23]
	v_mfma_f32_16x16x4_f32 v[16:19], v2, v30, v[16:19]
	v_mfma_f32_16x16x4_f32 v[20:23], v2, v54, v[20:23]
	v_mfma_f32_16x16x4_f32 v[16:19], v3, v31, v[16:19]
	v_mfma_f32_16x16x4_f32 v[20:23], v3, v55, v[20:23]
	v_mfma_f32_16x16x4_f32 v[16:19], v4, v32, v[16:19]
	v_mfma_f32_16x16x4_f32 v[20:23], v4, v56, v[20:23]
	v_mfma_f32_16x16x4_f32 v[16:19], v5, v33, v[16:19]
	v_mfma_f32_16x16x4_f32 v[20:23], v5, v57, v[20:23]
	v_mfma_f32_16x16x4_f32 v[16:19], v6, v34, v[16:19]
	v_mfma_f32_16x16x4_f32 v[20:23], v6, v58, v[20:23]
	v_mfma_f32_16x16x4_f32 v[16:19], v7, v35, v[16:19]
	v_mfma_f32_16x16x4_f32 v[20:23], v7, v59, v[20:23]
	v_mfma_f32_16x16x4_f32 v[16:19], v8, v36, v[16:19]
	v_mfma_f32_16x16x4_f32 v[20:23], v8, v60, v[20:23]
	v_mfma_f32_16x16x4_f32 v[16:19], v9, v37, v[16:19]
	v_mfma_f32_16x16x4_f32 v[20:23], v9, v61, v[20:23]
	v_mfma_f32_16x16x4_f32 v[16:19], v10, v38, v[16:19]
	v_mfma_f32_16x16x4_f32 v[20:23], v10, v62, v[20:23]
	v_mfma_f32_16x16x4_f32 v[16:19], v11, v39, v[16:19]
	v_mfma_f32_16x16x4_f32 v[20:23], v11, v63, v[20:23]
	v_mfma_f32_16x16x4_f32 v[16:19], v12, v40, v[16:19]
	v_mfma_f32_16x16x4_f32 v[20:23], v12, v64, v[20:23]
	v_mfma_f32_16x16x4_f32 v[16:19], v13, v41, v[16:19]
	v_mfma_f32_16x16x4_f32 v[20:23], v13, v65, v[20:23]
	v_mfma_f32_16x16x4_f32 v[16:19], v14, v42, v[16:19]
	v_mfma_f32_16x16x4_f32 v[20:23], v14, v66, v[20:23]
	v_mfma_f32_16x16x4_f32 v[16:19], v15, v43, v[16:19]
	v_mfma_f32_16x16x4_f32 v[20:23], v15, v67, v[20:23]
	s_waitcnt lgkmcnt(0)
	s_nop 9
	v_sub_f32_e32 v44, v24, v140
	v_sub_f32_e32 v45, v25, v140
	v_sub_f32_e32 v46, v26, v140
	v_sub_f32_e32 v47, v27, v140
	v_fma_f32 v44, v44, s47, v16
	v_fma_f32 v45, v45, s47, v17
	v_fma_f32 v46, v46, s47, v18
	v_fma_f32 v47, v47, s47, v19
	ds_write_b32 v139, v44 offset:0
	ds_write_b32 v139, v45 offset:4160
	ds_write_b32 v139, v46 offset:8320
	ds_write_b32 v139, v47 offset:12480
	v_sub_f32_e32 v44, v24, v141
	v_sub_f32_e32 v45, v25, v141
	v_sub_f32_e32 v46, v26, v141
	v_sub_f32_e32 v47, v27, v141
	v_fma_f32 v44, v44, s47, v20
	v_fma_f32 v45, v45, s47, v21
	v_fma_f32 v46, v46, s47, v22
	v_fma_f32 v47, v47, s47, v23
	ds_write_b32 v139, v44 offset:512
	ds_write_b32 v139, v45 offset:4672
	ds_write_b32 v139, v46 offset:8832
	ds_write_b32 v139, v47 offset:12992
	ds_read_b32 v140, v138 offset:1024
	ds_read_b32 v141, v138 offset:1536
	v_mfma_f32_16x16x4_f32 v[16:19], v0, v68, 0
	v_mfma_f32_16x16x4_f32 v[20:23], v0, v84, 0
	v_mfma_f32_16x16x4_f32 v[16:19], v1, v69, v[16:19]
	v_mfma_f32_16x16x4_f32 v[20:23], v1, v85, v[20:23]
	v_mfma_f32_16x16x4_f32 v[16:19], v2, v70, v[16:19]
	v_mfma_f32_16x16x4_f32 v[20:23], v2, v86, v[20:23]
	v_mfma_f32_16x16x4_f32 v[16:19], v3, v71, v[16:19]
	v_mfma_f32_16x16x4_f32 v[20:23], v3, v87, v[20:23]
	v_mfma_f32_16x16x4_f32 v[16:19], v4, v72, v[16:19]
	v_mfma_f32_16x16x4_f32 v[20:23], v4, v88, v[20:23]
	v_mfma_f32_16x16x4_f32 v[16:19], v5, v73, v[16:19]
	v_mfma_f32_16x16x4_f32 v[20:23], v5, v89, v[20:23]
	v_mfma_f32_16x16x4_f32 v[16:19], v6, v74, v[16:19]
	v_mfma_f32_16x16x4_f32 v[20:23], v6, v90, v[20:23]
	v_mfma_f32_16x16x4_f32 v[16:19], v7, v75, v[16:19]
	v_mfma_f32_16x16x4_f32 v[20:23], v7, v91, v[20:23]
	v_mfma_f32_16x16x4_f32 v[16:19], v8, v76, v[16:19]
	v_mfma_f32_16x16x4_f32 v[20:23], v8, v92, v[20:23]
	v_mfma_f32_16x16x4_f32 v[16:19], v9, v77, v[16:19]
	v_mfma_f32_16x16x4_f32 v[20:23], v9, v93, v[20:23]
	v_mfma_f32_16x16x4_f32 v[16:19], v10, v78, v[16:19]
	v_mfma_f32_16x16x4_f32 v[20:23], v10, v94, v[20:23]
	v_mfma_f32_16x16x4_f32 v[16:19], v11, v79, v[16:19]
	v_mfma_f32_16x16x4_f32 v[20:23], v11, v95, v[20:23]
	v_mfma_f32_16x16x4_f32 v[16:19], v12, v80, v[16:19]
	v_mfma_f32_16x16x4_f32 v[20:23], v12, v96, v[20:23]
	v_mfma_f32_16x16x4_f32 v[16:19], v13, v81, v[16:19]
	v_mfma_f32_16x16x4_f32 v[20:23], v13, v97, v[20:23]
	v_mfma_f32_16x16x4_f32 v[16:19], v14, v82, v[16:19]
	v_mfma_f32_16x16x4_f32 v[20:23], v14, v98, v[20:23]
	v_mfma_f32_16x16x4_f32 v[16:19], v15, v83, v[16:19]
	v_mfma_f32_16x16x4_f32 v[20:23], v15, v99, v[20:23]
	s_waitcnt lgkmcnt(0)
; #define LAS __attribute__((address_space(3)))
; __device__ __forceinline__ void attn_sample_unit(LAS unsigned char* lds, CArgsP a, int b, int h) {
;     ...
;     for (int j = tid; j < SA_NK; j += 512) {
;         const float* kp = j < PAST ? ck + (((size_t)b * PAST + j) * 8 + h) * 64 : nk + (size_t)(16 * b + (j - PAST)) * 512 + h * 64;
;         float acc[16];
; #pragma unroll
;         for (int t = 0; t < 16; ++t) acc[t] = 0.f;
; #pragma unroll
;         for (int hb = 0; hb < 2; ++hb) {
;             f32x4 kr[8];
; #pragma unroll
;             for (int i = 0; i < 8; ++i) kr[i] = *(const f32x4*)(kp + 32 * hb + 4 * i);
; #pragma unroll
;             for (int i = 0; i < 8; ++i) {
;                 asm volatile("" ::: "memory");
;                 const f32x4 k4 = kr[i];
; #pragma unroll
;                 for (int t = 0; t < 16; ++t) { const f32x4 q4 = *(const LAS f32x4*)(Qs + t * 64 + 32 * hb + 4 * i); acc[t] += (q4[0] * k4[0] + q4[1] * k4[1]) + (q4[2] * k4[2] + q4[3] * k4[3]); }
;             }
;         }
;         const float cj = C[j];
; #pragma unroll
;         for (int t = 0; t < 16; ++t) SC[t * SA_NK + j] = acc[t] + (C[PAST + t] - cj) * LOG2E;
	s_nop 9
	v_sub_f32_e32 v44, v24, v140
	v_sub_f32_e32 v45, v25, v140
	v_sub_f32_e32 v46, v26, v140
	v_sub_f32_e32 v47, v27, v140
	v_fma_f32 v44, v44, s47, v16
	v_fma_f32 v45, v45, s47, v17
	v_fma_f32 v46, v46, s47, v18
	v_fma_f32 v47, v47, s47, v19
	ds_write_b32 v139, v44 offset:1024
	ds_write_b32 v139, v45 offset:5184
	ds_write_b32 v139, v46 offset:9344
	ds_write_b32 v139, v47 offset:13504
	v_sub_f32_e32 v44, v24, v141
	v_sub_f32_e32 v45, v25, v141
	v_sub_f32_e32 v46, v26, v141
	v_sub_f32_e32 v47, v27, v141
	v_fma_f32 v44, v44, s47, v20
	v_fma_f32 v45, v45, s47, v21
	v_fma_f32 v46, v46, s47, v22
	v_fma_f32 v47, v47, s47, v23
	ds_write_b32 v139, v44 offset:1536
	ds_write_b32 v139, v45 offset:5696
	ds_write_b32 v139, v46 offset:9856
	ds_write_b32 v139, v47 offset:14016
	ds_read_b32 v140, v138 offset:2048
	ds_read_b32 v141, v138 offset:2560
	v_mfma_f32_16x16x4_f32 v[16:19], v0, v104, 0
	v_mfma_f32_16x16x4_f32 v[20:23], v0, v120, 0
	v_mfma_f32_16x16x4_f32 v[16:19], v1, v105, v[16:19]
	v_mfma_f32_16x16x4_f32 v[20:23], v1, v121, v[20:23]
	v_mfma_f32_16x16x4_f32 v[16:19], v2, v106, v[16:19]
	v_mfma_f32_16x16x4_f32 v[20:23], v2, v122, v[20:23]
	v_mfma_f32_16x16x4_f32 v[16:19], v3, v107, v[16:19]
	v_mfma_f32_16x16x4_f32 v[20:23], v3, v123, v[20:23]
	v_mfma_f32_16x16x4_f32 v[16:19], v4, v108, v[16:19]
	v_mfma_f32_16x16x4_f32 v[20:23], v4, v124, v[20:23]
	v_mfma_f32_16x16x4_f32 v[16:19], v5, v109, v[16:19]
	v_mfma_f32_16x16x4_f32 v[20:23], v5, v125, v[20:23]
	v_mfma_f32_16x16x4_f32 v[16:19], v6, v110, v[16:19]
	v_mfma_f32_16x16x4_f32 v[20:23], v6, v126, v[20:23]
	v_mfma_f32_16x16x4_f32 v[16:19], v7, v111, v[16:19]
	v_mfma_f32_16x16x4_f32 v[20:23], v7, v127, v[20:23]
	v_mfma_f32_16x16x4_f32 v[16:19], v8, v112, v[16:19]
	v_mfma_f32_16x16x4_f32 v[20:23], v8, v128, v[20:23]
	v_mfma_f32_16x16x4_f32 v[16:19], v9, v113, v[16:19]
	v_mfma_f32_16x16x4_f32 v[20:23], v9, v129, v[20:23]
	v_mfma_f32_16x16x4_f32 v[16:19], v10, v114, v[16:19]
	v_mfma_f32_16x16x4_f32 v[20:23], v10, v130, v[20:23]
	v_mfma_f32_16x16x4_f32 v[16:19], v11, v115, v[16:19]
	v_mfma_f32_16x16x4_f32 v[20:23], v11, v131, v[20:23]
	v_mfma_f32_16x16x4_f32 v[16:19], v12, v116, v[16:19]
	v_mfma_f32_16x16x4_f32 v[20:23], v12, v132, v[20:23]
	v_mfma_f32_16x16x4_f32 v[16:19], v13, v117, v[16:19]
	v_mfma_f32_16x16x4_f32 v[20:23], v13, v133, v[20:23]
	v_mfma_f32_16x16x4_f32 v[16:19], v14, v118, v[16:19]
	v_mfma_f32_16x16x4_f32 v[20:23], v14, v134, v[20:23]
	v_mfma_f32_16x16x4_f32 v[16:19], v15, v119, v[16:19]
	v_mfma_f32_16x16x4_f32 v[20:23], v15, v135, v[20:23]
	s_waitcnt lgkmcnt(0)
	s_nop 9
	v_sub_f32_e32 v44, v24, v140
	v_sub_f32_e32 v45, v25, v140
	v_sub_f32_e32 v46, v26, v140
	v_sub_f32_e32 v47, v27, v140
	v_fma_f32 v44, v44, s47, v16
	v_fma_f32 v45, v45, s47, v17
	v_fma_f32 v46, v46, s47, v18
	v_fma_f32 v47, v47, s47, v19
	ds_write_b32 v139, v44 offset:2048
	ds_write_b32 v139, v45 offset:6208
	ds_write_b32 v139, v46 offset:10368
	ds_write_b32 v139, v47 offset:14528
	v_sub_f32_e32 v44, v24, v141
	v_sub_f32_e32 v45, v25, v141
	v_sub_f32_e32 v46, v26, v141
	v_sub_f32_e32 v47, v27, v141
	v_fma_f32 v44, v44, s47, v20
	v_fma_f32 v45, v45, s47, v21
	v_fma_f32 v46, v46, s47, v22
	v_fma_f32 v47, v47, s47, v23
	ds_write_b32 v139, v44 offset:2560
	ds_write_b32 v139, v45 offset:6720
	ds_write_b32 v139, v46 offset:10880
	ds_write_b32 v139, v47 offset:15040
	ds_read_b32 v140, v138 offset:3072
	ds_read_b32 v141, v138 offset:3584
	v_mfma_f32_16x16x4_f32 v[16:19], v0, v202, 0
	v_mfma_f32_16x16x4_f32 v[20:23], v0, v218, 0
	v_mfma_f32_16x16x4_f32 v[16:19], v1, v203, v[16:19]
	v_mfma_f32_16x16x4_f32 v[20:23], v1, v219, v[20:23]
	v_mfma_f32_16x16x4_f32 v[16:19], v2, v204, v[16:19]
	v_mfma_f32_16x16x4_f32 v[20:23], v2, v220, v[20:23]
	v_mfma_f32_16x16x4_f32 v[16:19], v3, v205, v[16:19]
	v_mfma_f32_16x16x4_f32 v[20:23], v3, v221, v[20:23]
	v_mfma_f32_16x16x4_f32 v[16:19], v4, v206, v[16:19]
	v_mfma_f32_16x16x4_f32 v[20:23], v4, v222, v[20:23]
	v_mfma_f32_16x16x4_f32 v[16:19], v5, v207, v[16:19]
	v_mfma_f32_16x16x4_f32 v[20:23], v5, v223, v[20:23]
	v_mfma_f32_16x16x4_f32 v[16:19], v6, v208, v[16:19]
	v_mfma_f32_16x16x4_f32 v[20:23], v6, v224, v[20:23]
	v_mfma_f32_16x16x4_f32 v[16:19], v7, v209, v[16:19]
	v_mfma_f32_16x16x4_f32 v[20:23], v7, v225, v[20:23]
	v_mfma_f32_16x16x4_f32 v[16:19], v8, v210, v[16:19]
	v_mfma_f32_16x16x4_f32 v[20:23], v8, v226, v[20:23]
	v_mfma_f32_16x16x4_f32 v[16:19], v9, v211, v[16:19]
	v_mfma_f32_16x16x4_f32 v[20:23], v9, v227, v[20:23]
	v_mfma_f32_16x16x4_f32 v[16:19], v10, v212, v[16:19]
	v_mfma_f32_16x16x4_f32 v[20:23], v10, v228, v[20:23]
	v_mfma_f32_16x16x4_f32 v[16:19], v11, v213, v[16:19]
	v_mfma_f32_16x16x4_f32 v[20:23], v11, v229, v[20:23]
	v_mfma_f32_16x16x4_f32 v[16:19], v12, v214, v[16:19]
	v_mfma_f32_16x16x4_f32 v[20:23], v12, v230, v[20:23]
	v_mfma_f32_16x16x4_f32 v[16:19], v13, v215, v[16:19]
	v_mfma_f32_16x16x4_f32 v[20:23], v13, v231, v[20:23]
	v_mfma_f32_16x16x4_f32 v[16:19], v14, v216, v[16:19]
	v_mfma_f32_16x16x4_f32 v[20:23], v14, v232, v[20:23]
	v_mfma_f32_16x16x4_f32 v[16:19], v15, v217, v[16:19]
	v_mfma_f32_16x16x4_f32 v[20:23], v15, v233, v[20:23]
	s_waitcnt lgkmcnt(0)
	s_nop 9
	v_sub_f32_e32 v44, v24, v140
	v_sub_f32_e32 v45, v25, v140
	v_sub_f32_e32 v46, v26, v140
	v_sub_f32_e32 v47, v27, v140
	v_fma_f32 v44, v44, s47, v16
	v_fma_f32 v45, v45, s47, v17
	v_fma_f32 v46, v46, s47, v18
	v_fma_f32 v47, v47, s47, v19
	ds_write_b32 v139, v44 offset:3072
	ds_write_b32 v139, v45 offset:7232
	ds_write_b32 v139, v46 offset:11392
	ds_write_b32 v139, v47 offset:15552
	v_sub_f32_e32 v44, v24, v141
	v_sub_f32_e32 v45, v25, v141
	v_sub_f32_e32 v46, v26, v141
	v_sub_f32_e32 v47, v27, v141
	v_fma_f32 v44, v44, s47, v20
	v_fma_f32 v45, v45, s47, v21
	v_fma_f32 v46, v46, s47, v22
	v_fma_f32 v47, v47, s47, v23
	ds_write_b32 v139, v44 offset:3584
	ds_write_b32 v139, v45 offset:7744
	ds_write_b32 v139, v46 offset:11904
	ds_write_b32 v139, v47 offset:16064
	s_cmp_lg_u32 s46, 0
	s_cbranch_scc1 .Lqk_noext1
; #define LAS __attribute__((address_space(3)))
; __device__ __forceinline__ void attn_sample_unit(LAS unsigned char* lds, CArgsP a, int b, int h) {
;     ...
;     for (int j = tid; j < SA_NK; j += 512) {
;         const float* kp = j < PAST ? ck + (((size_t)b * PAST + j) * 8 + h) * 64 : nk + (size_t)(16 * b + (j - PAST)) * 512 + h * 64;
;         float acc[16];
; #pragma unroll
;         for (int t = 0; t < 16; ++t) acc[t] = 0.f;
; #pragma unroll
;         for (int hb = 0; hb < 2; ++hb) {
;             f32x4 kr[8];
; #pragma unroll
;             for (int i = 0; i < 8; ++i) kr[i] = *(const f32x4*)(kp + 32 * hb + 4 * i);
; #pragma unroll
;             for (int i = 0; i < 8; ++i) {
;                 asm volatile("" ::: "memory");
;                 const f32x4 k4 = kr[i];
; #pragma unroll
;                 for (int t = 0; t < 16; ++t) { const f32x4 q4 = *(const LAS f32x4*)(Qs + t * 64 + 32 * hb + 4 * i); acc[t] += (q4[0] * k4[0] + q4[1] * k4[1]) + (q4[2] * k4[2] + q4[3] * k4[3]); }
;             }
;         }
;         const float cj = C[j];
; #pragma unroll
;         for (int t = 0; t < 16; ++t) SC[t * SA_NK + j] = acc[t] + (C[PAST + t] - cj) * LOG2E;
;     ...
;         const float* vp = cv + ((size_t)b * PAST * 8 + h) * 64 + lane;
;         float vv[8], vn8[8];
; #pragma unroll
;         for (int i = 0; i < 8; ++i) vv[i] = vp[(size_t)(wid + 8 * i) * 512];
; #pragma unroll 1
;         for (int j0 = wid; j0 < PAST; j0 += 64) {
;             const int jn = (j0 + 64 < PAST) ? j0 + 64 : j0;
; #pragma unroll
;             for (int i = 0; i < 8; ++i) vn8[i] = vp[(size_t)(jn + 8 * i) * 512];
; #pragma unroll
;             for (int i = 0; i < 8; ++i) {
;                 asm volatile("" ::: "memory");
; #pragma unroll
;                 for (int t = 0; t < 16; ++t) acc[t] += SC[t * SA_NK + j0 + 8 * i] * vv[i];
;             }
; #pragma unroll
;             for (int i = 0; i < 8; ++i) vv[i] = vn8[i];
;         }
;         {
;             const float* vn = nv + (size_t)(16 * b) * 512 + h * 64 + lane;
;             const float v0 = vn[(size_t)wid * 512], v1 = vn[(size_t)(wid + 8) * 512];
	ds_read_b32 v142, v138 offset:4096
	v_mfma_f32_16x16x4_f32 v[16:19], v0, v234, 0
	v_mfma_f32_16x16x4_f32 v[16:19], v1, v235, v[16:19]
	v_mfma_f32_16x16x4_f32 v[16:19], v2, v236, v[16:19]
	v_mfma_f32_16x16x4_f32 v[16:19], v3, v237, v[16:19]
	v_mfma_f32_16x16x4_f32 v[16:19], v4, v238, v[16:19]
	v_mfma_f32_16x16x4_f32 v[16:19], v5, v239, v[16:19]
	v_mfma_f32_16x16x4_f32 v[16:19], v6, v240, v[16:19]
	v_mfma_f32_16x16x4_f32 v[16:19], v7, v241, v[16:19]
	v_mfma_f32_16x16x4_f32 v[16:19], v8, v242, v[16:19]
	v_mfma_f32_16x16x4_f32 v[16:19], v9, v243, v[16:19]
	v_mfma_f32_16x16x4_f32 v[16:19], v10, v244, v[16:19]
	v_mfma_f32_16x16x4_f32 v[16:19], v11, v245, v[16:19]
	v_mfma_f32_16x16x4_f32 v[16:19], v12, v246, v[16:19]
	v_mfma_f32_16x16x4_f32 v[16:19], v13, v247, v[16:19]
	v_mfma_f32_16x16x4_f32 v[16:19], v14, v248, v[16:19]
	v_mfma_f32_16x16x4_f32 v[16:19], v15, v249, v[16:19]
	s_waitcnt lgkmcnt(0)
	s_nop 9
	v_sub_f32_e32 v44, v24, v142
	v_sub_f32_e32 v45, v25, v142
	v_sub_f32_e32 v46, v26, v142
	v_sub_f32_e32 v47, v27, v142
	v_fma_f32 v44, v44, s47, v16
	v_fma_f32 v45, v45, s47, v17
	v_fma_f32 v46, v46, s47, v18
	v_fma_f32 v47, v47, s47, v19
	ds_write_b32 v139, v44 offset:4096
	ds_write_b32 v139, v45 offset:8256
	ds_write_b32 v139, v46 offset:12416
	ds_write_b32 v139, v47 offset:16576
	global_load_dwordx4 v[234:237], v136, s[44:45] offset:0
	global_load_dwordx4 v[238:241], v136, s[44:45] offset:2048
	global_load_dwordx4 v[242:245], v137, s[44:45] offset:0
	global_load_dwordx4 v[246:249], v137, s[44:45] offset:2048
.Lqk_noext1:
	s_add_u32 s48, s42, 0x0
	s_addc_u32 s49, s43, 0
	global_load_dwordx4 v[28:31], v136, s[48:49] offset:0
	global_load_dwordx4 v[32:35], v136, s[48:49] offset:2048
	global_load_dwordx4 v[36:39], v137, s[48:49] offset:0
	global_load_dwordx4 v[40:43], v137, s[48:49] offset:2048
	s_add_u32 s48, s42, 0x40000
	s_addc_u32 s49, s43, 0
	global_load_dwordx4 v[52:55], v136, s[48:49] offset:0
	global_load_dwordx4 v[56:59], v136, s[48:49] offset:2048
	global_load_dwordx4 v[60:63], v137, s[48:49] offset:0
	global_load_dwordx4 v[64:67], v137, s[48:49] offset:2048
	s_add_u32 s48, s42, 0x80000
	s_addc_u32 s49, s43, 0
	global_load_dwordx4 v[68:71], v136, s[48:49] offset:0
	global_load_dwordx4 v[72:75], v136, s[48:49] offset:2048
	global_load_dwordx4 v[76:79], v137, s[48:49] offset:0
	global_load_dwordx4 v[80:83], v137, s[48:49] offset:2048
	s_add_u32 s48, s42, 0xc0000
	s_addc_u32 s49, s43, 0
	global_load_dwordx4 v[84:87], v136, s[48:49] offset:0
	global_load_dwordx4 v[88:91], v136, s[48:49] offset:2048
	global_load_dwordx4 v[92:95], v137, s[48:49] offset:0
	global_load_dwordx4 v[96:99], v137, s[48:49] offset:2048
	s_add_u32 s48, s42, 0x100000
	s_addc_u32 s49, s43, 0
	global_load_dwordx4 v[104:107], v136, s[48:49] offset:0
	global_load_dwordx4 v[108:111], v136, s[48:49] offset:2048
	global_load_dwordx4 v[112:115], v137, s[48:49] offset:0
	global_load_dwordx4 v[116:119], v137, s[48:49] offset:2048
	s_add_u32 s48, s42, 0x140000
	s_addc_u32 s49, s43, 0
	global_load_dwordx4 v[120:123], v136, s[48:49] offset:0
	global_load_dwordx4 v[124:127], v136, s[48:49] offset:2048
	global_load_dwordx4 v[128:131], v137, s[48:49] offset:0
	global_load_dwordx4 v[132:135], v137, s[48:49] offset:2048
	s_add_u32 s48, s42, 0x180000
	s_addc_u32 s49, s43, 0
	global_load_dwordx4 v[202:205], v136, s[48:49] offset:0
	global_load_dwordx4 v[206:209], v136, s[48:49] offset:2048
	global_load_dwordx4 v[210:213], v137, s[48:49] offset:0
	global_load_dwordx4 v[214:217], v137, s[48:49] offset:2048
	s_add_u32 s48, s42, 0x1c0000
	s_addc_u32 s49, s43, 0
	global_load_dwordx4 v[218:221], v136, s[48:49] offset:0
	global_load_dwordx4 v[222:225], v136, s[48:49] offset:2048
	global_load_dwordx4 v[226:229], v137, s[48:49] offset:0
	global_load_dwordx4 v[230:233], v137, s[48:49] offset:2048
	s_movk_i32 s3, 0x2080
	v_mad_u32_u24 v6, v50, s3, v165
	v_add_u32_e32 v7, 0, v6
	v_lshlrev_b32_e32 v8, 1, v50
	v_add_u32_e32 v0, 0x2100, v7
	v_mul_u32_u24_e32 v4, 0x2080, v50
	v_or_b32_e32 v1, 0x400, v8
	v_mov_b32_e32 v2, 0xff800000
	s_mov_b64 s[6:7], 0
	s_movk_i32 s3, 0x3cf
	v_mov_b32_e32 v5, v0
	v_mov_b32_e32 v9, v148
	v_mov_b32_e32 v3, 0xff800000
	s_waitcnt lgkmcnt(0)
	s_barrier
	s_branch .LBB0_1354

; __device__ __forceinline__ void attn_sample_unit(LAS unsigned char* lds, CArgsP a, int b, int h) {
;     ...
;     {
;         float acc[16];
; #pragma unroll
;         for (int t = 0; t < 16; ++t) acc[t] = 0.f;
;         const float* vp = cv + ((size_t)b * PAST * 8 + h) * 64 + lane;
;         float vv[8], vn8[8];
; #pragma unroll
;         for (int i = 0; i < 8; ++i) vv[i] = vp[(size_t)(wid + 8 * i) * 512];
; #pragma unroll 1
;         for (int j0 = wid; j0 < PAST; j0 += 64) {
;             const int jn = (j0 + 64 < PAST) ? j0 + 64 : j0;
; #pragma unroll
;             for (int i = 0; i < 8; ++i) vn8[i] = vp[(size_t)(jn + 8 * i) * 512];
; #pragma unroll
;             for (int i = 0; i < 8; ++i) {
;                 asm volatile("" ::: "memory");
; #pragma unroll
;                 for (int t = 0; t < 16; ++t) acc[t] += SC[t * SA_NK + j0 + 8 * i] * vv[i];
;             }
; #pragma unroll
;             for (int i = 0; i < 8; ++i) vv[i] = vn8[i];
;         }
.LBB0_1430:
	s_or_b64 exec, exec, s[8:9]
	s_lshl_b64 s[4:5], s[24:25], 21
	s_add_u32 s4, s18, s4
	s_addc_u32 s5, s19, s5
	s_lshl_b32 s3, s1, 2
	s_add_u32 s4, s4, s3
	v_mov_b32_e32 v3, 0
	s_addc_u32 s5, s5, 0
	v_mov_b32_e32 v101, v3
	v_lshl_add_u64 v[4:5], s[4:5], 0, v[100:101]
	v_lshlrev_b32_e32 v2, 11, v50
	v_lshl_add_u64 v[0:1], v[4:5], 0, v[2:3]
	s_mov_b32 s4, 0x1c000
	v_add_co_u32_e32 v6, vcc, s4, v0
	s_mov_b32 s5, 0x18000
	s_nop 0
	v_addc_co_u32_e32 v7, vcc, 0, v1, vcc
	v_add_co_u32_e32 v8, vcc, s5, v0
	s_mov_b32 s10, 0x14000
	s_nop 0
	v_addc_co_u32_e32 v9, vcc, 0, v1, vcc
	v_add_co_u32_e32 v10, vcc, s10, v0
	s_mov_b32 s11, 0x10000
	s_nop 0
	v_addc_co_u32_e32 v11, vcc, 0, v1, vcc
	v_add_co_u32_e32 v12, vcc, s11, v0
	s_mov_b32 s16, 0xc000
	s_nop 0
	v_addc_co_u32_e32 v13, vcc, 0, v1, vcc
	v_add_co_u32_e32 v14, vcc, s16, v0
	s_mov_b32 s17, 0x8000
	s_nop 0
	v_addc_co_u32_e32 v15, vcc, 0, v1, vcc
	v_add_co_u32_e32 v16, vcc, s17, v0
	s_movk_i32 s18, 0x4000
	s_nop 0
	v_addc_co_u32_e32 v17, vcc, 0, v1, vcc
	v_add_co_u32_e32 v18, vcc, s18, v0
	s_waitcnt lgkmcnt(0)
	s_barrier
	v_lshrrev_b32_e32 v140, 4, v148
	v_and_b32_e32 v141, 15, v148
	s_lshl_b32 s48, s46, 6
	v_mul_u32_u24_e32 v138, 0x1040, v141
	v_lshl_add_u32 v138, v140, 4, v138
	v_add_u32_e32 v138, s48, v138
	v_add_u32_e32 v138, 0x2100, v138
	s_lshl_b32 s48, s46, 12
	v_lshlrev_b32_e32 v139, 10, v140
	v_lshl_add_u32 v139, v141, 4, v139
	v_add_u32_e32 v139, s48, v139
	v_add_u32_e32 v139, 0x2100, v139
	ds_read_b128 v[16:19], v138 offset:0
	ds_read_b128 v[20:23], v138 offset:512
	ds_read_b128 v[24:27], v138 offset:1024
	s_waitcnt vmcnt(28)
	s_waitcnt lgkmcnt(2)
	v_mfma_f32_16x16x4_f32 v[0:3], v16, v28, 0
	v_mfma_f32_16x16x4_f32 v[4:7], v16, v29, 0
	v_mfma_f32_16x16x4_f32 v[8:11], v16, v30, 0
	v_mfma_f32_16x16x4_f32 v[12:15], v16, v31, 0
	v_mfma_f32_16x16x4_f32 v[0:3], v17, v32, v[0:3]
	v_mfma_f32_16x16x4_f32 v[4:7], v17, v33, v[4:7]
	v_mfma_f32_16x16x4_f32 v[8:11], v17, v34, v[8:11]
	v_mfma_f32_16x16x4_f32 v[12:15], v17, v35, v[12:15]
	v_mfma_f32_16x16x4_f32 v[0:3], v18, v36, v[0:3]
	v_mfma_f32_16x16x4_f32 v[4:7], v18, v37, v[4:7]
	v_mfma_f32_16x16x4_f32 v[8:11], v18, v38, v[8:11]
	v_mfma_f32_16x16x4_f32 v[12:15], v18, v39, v[12:15]
	v_mfma_f32_16x16x4_f32 v[0:3], v19, v40, v[0:3]
	v_mfma_f32_16x16x4_f32 v[4:7], v19, v41, v[4:7]
	v_mfma_f32_16x16x4_f32 v[8:11], v19, v42, v[8:11]
	v_mfma_f32_16x16x4_f32 v[12:15], v19, v43, v[12:15]
	ds_read_b128 v[44:47], v138 offset:1536
	s_waitcnt vmcnt(24)
	s_waitcnt lgkmcnt(2)
	v_mfma_f32_16x16x4_f32 v[0:3], v20, v52, v[0:3]
	v_mfma_f32_16x16x4_f32 v[4:7], v20, v53, v[4:7]
	v_mfma_f32_16x16x4_f32 v[8:11], v20, v54, v[8:11]
	v_mfma_f32_16x16x4_f32 v[12:15], v20, v55, v[12:15]
	v_mfma_f32_16x16x4_f32 v[0:3], v21, v56, v[0:3]
	v_mfma_f32_16x16x4_f32 v[4:7], v21, v57, v[4:7]
	v_mfma_f32_16x16x4_f32 v[8:11], v21, v58, v[8:11]
	v_mfma_f32_16x16x4_f32 v[12:15], v21, v59, v[12:15]
	v_mfma_f32_16x16x4_f32 v[0:3], v22, v60, v[0:3]
	v_mfma_f32_16x16x4_f32 v[4:7], v22, v61, v[4:7]
	v_mfma_f32_16x16x4_f32 v[8:11], v22, v62, v[8:11]
	v_mfma_f32_16x16x4_f32 v[12:15], v22, v63, v[12:15]
	v_mfma_f32_16x16x4_f32 v[0:3], v23, v64, v[0:3]
	v_mfma_f32_16x16x4_f32 v[4:7], v23, v65, v[4:7]
	v_mfma_f32_16x16x4_f32 v[8:11], v23, v66, v[8:11]
	v_mfma_f32_16x16x4_f32 v[12:15], v23, v67, v[12:15]
	ds_read_b128 v[16:19], v138 offset:2048
	s_waitcnt vmcnt(20)
	s_waitcnt lgkmcnt(2)
	v_mfma_f32_16x16x4_f32 v[0:3], v24, v68, v[0:3]
	v_mfma_f32_16x16x4_f32 v[4:7], v24, v69, v[4:7]
	v_mfma_f32_16x16x4_f32 v[8:11], v24, v70, v[8:11]
	v_mfma_f32_16x16x4_f32 v[12:15], v24, v71, v[12:15]
	v_mfma_f32_16x16x4_f32 v[0:3], v25, v72, v[0:3]
	v_mfma_f32_16x16x4_f32 v[4:7], v25, v73, v[4:7]
	v_mfma_f32_16x16x4_f32 v[8:11], v25, v74, v[8:11]
	v_mfma_f32_16x16x4_f32 v[12:15], v25, v75, v[12:15]
	v_mfma_f32_16x16x4_f32 v[0:3], v26, v76, v[0:3]
	v_mfma_f32_16x16x4_f32 v[4:7], v26, v77, v[4:7]
	v_mfma_f32_16x16x4_f32 v[8:11], v26, v78, v[8:11]
	v_mfma_f32_16x16x4_f32 v[12:15], v26, v79, v[12:15]
	v_mfma_f32_16x16x4_f32 v[0:3], v27, v80, v[0:3]
	v_mfma_f32_16x16x4_f32 v[4:7], v27, v81, v[4:7]
	v_mfma_f32_16x16x4_f32 v[8:11], v27, v82, v[8:11]
	v_mfma_f32_16x16x4_f32 v[12:15], v27, v83, v[12:15]
	ds_read_b128 v[20:23], v138 offset:2560
	s_waitcnt vmcnt(16)
	s_waitcnt lgkmcnt(2)
	v_mfma_f32_16x16x4_f32 v[0:3], v44, v84, v[0:3]
	v_mfma_f32_16x16x4_f32 v[4:7], v44, v85, v[4:7]
	v_mfma_f32_16x16x4_f32 v[8:11], v44, v86, v[8:11]
	v_mfma_f32_16x16x4_f32 v[12:15], v44, v87, v[12:15]
	v_mfma_f32_16x16x4_f32 v[0:3], v45, v88, v[0:3]
	v_mfma_f32_16x16x4_f32 v[4:7], v45, v89, v[4:7]
	v_mfma_f32_16x16x4_f32 v[8:11], v45, v90, v[8:11]
	v_mfma_f32_16x16x4_f32 v[12:15], v45, v91, v[12:15]
	v_mfma_f32_16x16x4_f32 v[0:3], v46, v92, v[0:3]
	v_mfma_f32_16x16x4_f32 v[4:7], v46, v93, v[4:7]
	v_mfma_f32_16x16x4_f32 v[8:11], v46, v94, v[8:11]
	v_mfma_f32_16x16x4_f32 v[12:15], v46, v95, v[12:15]
	v_mfma_f32_16x16x4_f32 v[0:3], v47, v96, v[0:3]
	v_mfma_f32_16x16x4_f32 v[4:7], v47, v97, v[4:7]
	v_mfma_f32_16x16x4_f32 v[8:11], v47, v98, v[8:11]
	v_mfma_f32_16x16x4_f32 v[12:15], v47, v99, v[12:15]
	ds_read_b128 v[24:27], v138 offset:3072
	s_waitcnt vmcnt(12)
	s_waitcnt lgkmcnt(2)
	v_mfma_f32_16x16x4_f32 v[0:3], v16, v104, v[0:3]
	v_mfma_f32_16x16x4_f32 v[4:7], v16, v105, v[4:7]
	v_mfma_f32_16x16x4_f32 v[8:11], v16, v106, v[8:11]
	v_mfma_f32_16x16x4_f32 v[12:15], v16, v107, v[12:15]
	v_mfma_f32_16x16x4_f32 v[0:3], v17, v108, v[0:3]
	v_mfma_f32_16x16x4_f32 v[4:7], v17, v109, v[4:7]
	v_mfma_f32_16x16x4_f32 v[8:11], v17, v110, v[8:11]
	v_mfma_f32_16x16x4_f32 v[12:15], v17, v111, v[12:15]
	v_mfma_f32_16x16x4_f32 v[0:3], v18, v112, v[0:3]
	v_mfma_f32_16x16x4_f32 v[4:7], v18, v113, v[4:7]
	v_mfma_f32_16x16x4_f32 v[8:11], v18, v114, v[8:11]
	v_mfma_f32_16x16x4_f32 v[12:15], v18, v115, v[12:15]
	v_mfma_f32_16x16x4_f32 v[0:3], v19, v116, v[0:3]
	v_mfma_f32_16x16x4_f32 v[4:7], v19, v117, v[4:7]
	v_mfma_f32_16x16x4_f32 v[8:11], v19, v118, v[8:11]
	v_mfma_f32_16x16x4_f32 v[12:15], v19, v119, v[12:15]
	ds_read_b128 v[44:47], v138 offset:3584
	s_waitcnt vmcnt(8)
; #define LAS __attribute__((address_space(3)))
; __device__ __forceinline__ unsigned pk2(float lo, float hi) { return f2bf(lo) | (f2bf(hi) << 16); }
; __device__ __forceinline__ void attn_sample_unit(LAS unsigned char* lds, CArgsP a, int b, int h) {
;     ...
;             for (int i = 0; i < 8; ++i) {
;                 asm volatile("" ::: "memory");
; #pragma unroll
;                 for (int t = 0; t < 16; ++t) acc[t] += SC[t * SA_NK + j0 + 8 * i] * vv[i];
;             }
; #pragma unroll
;             for (int i = 0; i < 8; ++i) vv[i] = vn8[i];
;         }
;         {
;             const float* vn = nv + (size_t)(16 * b) * 512 + h * 64 + lane;
;             const float v0 = vn[(size_t)wid * 512], v1 = vn[(size_t)(wid + 8) * 512];
; #pragma unroll
;             for (int t = 0; t < 16; ++t) acc[t] += SC[t * SA_NK + PAST + wid] * v0 + SC[t * SA_NK + PAST + wid + 8] * v1;
;         }
;         __syncthreads();
;         LAS float* red = SC;
; #pragma unroll
;         for (int t = 0; t < 16; ++t) red[(wid * 16 + t) * 64 + lane] = acc[t];
;         __syncthreads();
;         {
;             const int t = tid >> 5, d = 2 * (tid & 31);
;             float a0 = 0.f, a1 = 0.f;
; #pragma unroll
;             for (int w = 0; w < 8; ++w) { a0 += red[(w * 16 + t) * 64 + d]; a1 += red[(w * 16 + t) * 64 + d + 1]; }
;             *(unsigned*)(MIX + (size_t)(TP + 16 * b + t) * DM + h * 64 + d) = pk2(a0, a1);
	s_waitcnt lgkmcnt(2)
	v_mfma_f32_16x16x4_f32 v[0:3], v20, v120, v[0:3]
	v_mfma_f32_16x16x4_f32 v[4:7], v20, v121, v[4:7]
	v_mfma_f32_16x16x4_f32 v[8:11], v20, v122, v[8:11]
	v_mfma_f32_16x16x4_f32 v[12:15], v20, v123, v[12:15]
	v_mfma_f32_16x16x4_f32 v[0:3], v21, v124, v[0:3]
	v_mfma_f32_16x16x4_f32 v[4:7], v21, v125, v[4:7]
	v_mfma_f32_16x16x4_f32 v[8:11], v21, v126, v[8:11]
	v_mfma_f32_16x16x4_f32 v[12:15], v21, v127, v[12:15]
	v_mfma_f32_16x16x4_f32 v[0:3], v22, v128, v[0:3]
	v_mfma_f32_16x16x4_f32 v[4:7], v22, v129, v[4:7]
	v_mfma_f32_16x16x4_f32 v[8:11], v22, v130, v[8:11]
	v_mfma_f32_16x16x4_f32 v[12:15], v22, v131, v[12:15]
	v_mfma_f32_16x16x4_f32 v[0:3], v23, v132, v[0:3]
	v_mfma_f32_16x16x4_f32 v[4:7], v23, v133, v[4:7]
	v_mfma_f32_16x16x4_f32 v[8:11], v23, v134, v[8:11]
	v_mfma_f32_16x16x4_f32 v[12:15], v23, v135, v[12:15]
	s_waitcnt vmcnt(4)
	s_waitcnt lgkmcnt(1)
	v_mfma_f32_16x16x4_f32 v[0:3], v24, v202, v[0:3]
	v_mfma_f32_16x16x4_f32 v[4:7], v24, v203, v[4:7]
	v_mfma_f32_16x16x4_f32 v[8:11], v24, v204, v[8:11]
	v_mfma_f32_16x16x4_f32 v[12:15], v24, v205, v[12:15]
	v_mfma_f32_16x16x4_f32 v[0:3], v25, v206, v[0:3]
	v_mfma_f32_16x16x4_f32 v[4:7], v25, v207, v[4:7]
	v_mfma_f32_16x16x4_f32 v[8:11], v25, v208, v[8:11]
	v_mfma_f32_16x16x4_f32 v[12:15], v25, v209, v[12:15]
	v_mfma_f32_16x16x4_f32 v[0:3], v26, v210, v[0:3]
	v_mfma_f32_16x16x4_f32 v[4:7], v26, v211, v[4:7]
	v_mfma_f32_16x16x4_f32 v[8:11], v26, v212, v[8:11]
	v_mfma_f32_16x16x4_f32 v[12:15], v26, v213, v[12:15]
	v_mfma_f32_16x16x4_f32 v[0:3], v27, v214, v[0:3]
	v_mfma_f32_16x16x4_f32 v[4:7], v27, v215, v[4:7]
	v_mfma_f32_16x16x4_f32 v[8:11], v27, v216, v[8:11]
	v_mfma_f32_16x16x4_f32 v[12:15], v27, v217, v[12:15]
	s_waitcnt vmcnt(0)
	s_waitcnt lgkmcnt(0)
	v_mfma_f32_16x16x4_f32 v[0:3], v44, v218, v[0:3]
	v_mfma_f32_16x16x4_f32 v[4:7], v44, v219, v[4:7]
	v_mfma_f32_16x16x4_f32 v[8:11], v44, v220, v[8:11]
	v_mfma_f32_16x16x4_f32 v[12:15], v44, v221, v[12:15]
	v_mfma_f32_16x16x4_f32 v[0:3], v45, v222, v[0:3]
	v_mfma_f32_16x16x4_f32 v[4:7], v45, v223, v[4:7]
	v_mfma_f32_16x16x4_f32 v[8:11], v45, v224, v[8:11]
	v_mfma_f32_16x16x4_f32 v[12:15], v45, v225, v[12:15]
	v_mfma_f32_16x16x4_f32 v[0:3], v46, v226, v[0:3]
	v_mfma_f32_16x16x4_f32 v[4:7], v46, v227, v[4:7]
	v_mfma_f32_16x16x4_f32 v[8:11], v46, v228, v[8:11]
	v_mfma_f32_16x16x4_f32 v[12:15], v46, v229, v[12:15]
	v_mfma_f32_16x16x4_f32 v[0:3], v47, v230, v[0:3]
	v_mfma_f32_16x16x4_f32 v[4:7], v47, v231, v[4:7]
	v_mfma_f32_16x16x4_f32 v[8:11], v47, v232, v[8:11]
	v_mfma_f32_16x16x4_f32 v[12:15], v47, v233, v[12:15]
	s_cmp_lg_u32 s46, 0
	s_cbranch_scc1 .Lpv_noext
	ds_read_b128 v[16:19], v138 offset:4096
	s_waitcnt lgkmcnt(0)
	v_mfma_f32_16x16x4_f32 v[0:3], v16, v234, v[0:3]
	v_mfma_f32_16x16x4_f32 v[4:7], v16, v235, v[4:7]
	v_mfma_f32_16x16x4_f32 v[8:11], v16, v236, v[8:11]
	v_mfma_f32_16x16x4_f32 v[12:15], v16, v237, v[12:15]
	v_mfma_f32_16x16x4_f32 v[0:3], v17, v238, v[0:3]
	v_mfma_f32_16x16x4_f32 v[4:7], v17, v239, v[4:7]
	v_mfma_f32_16x16x4_f32 v[8:11], v17, v240, v[8:11]
	v_mfma_f32_16x16x4_f32 v[12:15], v17, v241, v[12:15]
	v_mfma_f32_16x16x4_f32 v[0:3], v18, v242, v[0:3]
	v_mfma_f32_16x16x4_f32 v[4:7], v18, v243, v[4:7]
	v_mfma_f32_16x16x4_f32 v[8:11], v18, v244, v[8:11]
	v_mfma_f32_16x16x4_f32 v[12:15], v18, v245, v[12:15]
	v_mfma_f32_16x16x4_f32 v[0:3], v19, v246, v[0:3]
	v_mfma_f32_16x16x4_f32 v[4:7], v19, v247, v[4:7]
	v_mfma_f32_16x16x4_f32 v[8:11], v19, v248, v[8:11]
	v_mfma_f32_16x16x4_f32 v[12:15], v19, v249, v[12:15]
.Lpv_noext:
	s_nop 9
	s_barrier
	ds_write_b32 v139, v0 offset:0
	ds_write_b32 v139, v1 offset:256
	ds_write_b32 v139, v2 offset:512
	ds_write_b32 v139, v3 offset:768
	ds_write_b32 v139, v4 offset:4
	ds_write_b32 v139, v5 offset:260
	ds_write_b32 v139, v6 offset:516
	ds_write_b32 v139, v7 offset:772
	ds_write_b32 v139, v8 offset:8
	ds_write_b32 v139, v9 offset:264
	ds_write_b32 v139, v10 offset:520
	ds_write_b32 v139, v11 offset:776
	ds_write_b32 v139, v12 offset:12
	ds_write_b32 v139, v13 offset:268
	ds_write_b32 v139, v14 offset:524
	ds_write_b32 v139, v15 offset:780
	s_movk_i32 s3, 0x7fff
	s_mov_b32 s5, 0
	s_lshl_b32 s4, s1, 1
	v_mov_b32_e32 v101, 0
	v_lshlrev_b32_e32 v0, 1, v164
	v_lshrrev_b32_e32 v14, 5, v164
	v_and_b32_e32 v15, 62, v0
	v_lshlrev_b32_e32 v0, 8, v14
	v_lshlrev_b32_e32 v1, 2, v15
	v_add3_u32 v0, 0, v0, v1
	v_add_u32_e32 v16, 0x100, v0
	s_waitcnt lgkmcnt(0)
	s_barrier
	ds_read2st64_b64 v[0:3], v16 offset0:16 offset1:24
	ds_read2st64_b64 v[4:7], v16 offset0:32 offset1:40
	ds_read2st64_b64 v[8:11], v16 offset0:48 offset1:56
	s_waitcnt lgkmcnt(2)
	v_pk_add_f32 v[0:1], v[0:1], 0 op_sel_hi:[1,0]
	s_nop 0
	v_pk_add_f32 v[12:13], v[0:1], v[2:3]
	ds_read2st64_b64 v[0:3], v16 offset0:64 offset1:72
	s_waitcnt lgkmcnt(2)
	v_pk_add_f32 v[4:5], v[12:13], v[4:5]
	s_nop 0
	v_pk_add_f32 v[4:5], v[4:5], v[6:7]
	s_waitcnt lgkmcnt(1)
	v_pk_add_f32 v[4:5], v[4:5], v[8:9]
	s_nop 0
	v_pk_add_f32 v[4:5], v[4:5], v[10:11]
	s_waitcnt lgkmcnt(0)
	v_pk_add_f32 v[0:1], v[4:5], v[0:1]
	s_nop 0
	v_pk_add_f32 v[0:1], v[0:1], v[2:3]
	v_mov_b32_e32 v2, 1
	v_and_b32_sdwa v3, v1, v2 dst_sel:DWORD dst_unused:UNUSED_PAD src0_sel:WORD_1 src1_sel:DWORD
	v_and_b32_sdwa v2, v0, v2 dst_sel:DWORD dst_unused:UNUSED_PAD src0_sel:WORD_1 src1_sel:DWORD
	v_add3_u32 v0, v0, v2, s3
	v_add3_u32 v1, v1, v3, s3
	v_lshrrev_b32_e32 v0, 16, v0
	s_mov_b32 s3, 0xffff0000
	v_and_or_b32 v4, v1, s3, v0
	v_add_u32_e32 v0, s0, v14
	v_bfrev_b32_e32 v1, 64
	v_lshl_add_u32 v0, v0, 11, v1
	v_mov_b32_e32 v1, v101
	v_lshl_add_u64 v[0:1], s[14:15], 0, v[0:1]
	v_lshl_add_u64 v[0:1], v[0:1], 0, s[4:5]
	v_lshlrev_b32_e32 v2, 1, v15
	v_mov_b32_e32 v3, v101
	v_lshl_add_u64 v[0:1], v[0:1], 0, v[2:3]
	v_add_co_u32_e32 v0, vcc, 0x2f00000, v0
	s_nop 1
	v_addc_co_u32_e32 v1, vcc, 0, v1, vcc
	global_store_dword v[0:1], v4, off
